# XCD seam: L1 invalidate issued before the arrival atomic instead of after the release
# speedup vs baseline: 1.0130x; 1.0130x over previous
; __device__ __forceinline__ unsigned xb_ld(unsigned* p)              { return __hip_atomic_load(p, __ATOMIC_RELAXED, __HIP_MEMORY_SCOPE_AGENT); }
; __device__ __forceinline__ unsigned xb_add(unsigned* p, unsigned v) { return __hip_atomic_fetch_add(p, v, __ATOMIC_RELAXED, __HIP_MEMORY_SCOPE_AGENT); }
; #define XB_SPIN(cond, bar) do { unsigned _sp = 0; while (cond) { __builtin_amdgcn_s_sleep(1); \
;     if ((++_sp & 255u) == 0u) { if (xb_ld(&(bar)[XB_TMO])) break; if (_sp > XB_SPIN_CAP) { atomicAdd(&(bar)[XB_TMO], 1u); break; } } } } while (0)
; __device__ __forceinline__ void xcc_barrier(unsigned* bar, unsigned x, unsigned nloc) {
;     asm volatile("s_waitcnt vmcnt(0)" ::: "memory");
;     __syncthreads();
;     if (threadIdx.x == 0) {
;         __builtin_amdgcn_s_waitcnt(0);
;         const unsigned old = xb_add(&bar[XL_SUB(x)], 1u), gen = old / nloc;
;         if (old + 1u == (gen + 1u) * nloc) xb_add(&bar[XL_GEN(x)], 1u); else XB_SPIN(xb_ld(&bar[XL_GEN(x)]) == gen, bar);
;         __builtin_amdgcn_fence(__ATOMIC_ACQUIRE, "agent");
;         asm volatile("s_waitcnt vmcnt(0)" ::: "memory");
;     }
;     __syncthreads();
; }
.LBB0_70:
	s_and_b64 vcc, exec, s[0:1]
	s_cbranch_vccz .LBB0_88
	s_waitcnt vmcnt(0)
	s_waitcnt lgkmcnt(0)
	v_readfirstlane_b32 s14, v3
	v_readfirstlane_b32 s15, v2
	s_barrier
	s_and_saveexec_b64 s[0:1], s[60:61]
	s_cbranch_execz .LBB0_87
	v_readlane_b32 s4, v254, 22
	s_lshl_b32 s4, s4, 8
	s_and_b32 s4, s4, 0x700
	s_add_u32 s4, s15, s4
	s_addc_u32 s5, s14, 0
	v_mov_b32_e32 v0, s4
	v_add_co_u32_e32 v2, vcc, 0x19704000, v0
	v_mov_b32_e32 v0, s5
	s_nop 0
	v_addc_co_u32_e32 v3, vcc, 0, v0, vcc
	s_waitcnt vmcnt(0) expcnt(0) lgkmcnt(0)
	buffer_inv sc1
	flat_atomic_add v0, v[2:3], v223 sc0
	s_add_u32 s6, s4, 0x19705000
	s_addc_u32 s7, s5, 0
	s_mov_b64 s[10:11], -1
	s_waitcnt vmcnt(0) lgkmcnt(0)
	v_mul_hi_u32 v2, v0, v222
	v_mul_lo_u32 v4, v2, s65
	v_add_u32_e32 v3, 1, v0
	v_sub_u32_e32 v0, v0, v4
	v_add_u32_e32 v5, 1, v2
	v_cmp_le_u32_e32 vcc, s65, v0
	v_subrev_u32_e32 v4, s65, v0
	s_nop 0
	v_cndmask_b32_e32 v2, v2, v5, vcc
	v_cndmask_b32_e32 v0, v0, v4, vcc
	v_add_u32_e32 v4, 1, v2
	v_cmp_le_u32_e32 vcc, s65, v0
	s_nop 1
	v_cndmask_b32_e32 v0, v2, v4, vcc
	v_mul_lo_u32 v2, s65, v0
	v_add_u32_e32 v2, s65, v2
	v_cmp_ne_u32_e32 vcc, v3, v2
	v_mov_b64_e32 v[2:3], s[6:7]
	s_and_saveexec_b64 s[8:9], vcc
	s_cbranch_execz .LBB0_84
	v_mov_b64_e32 v[2:3], s[6:7]
	flat_load_dword v2, v[2:3] sc1
	s_mov_b64 s[4:5], 0
	s_waitcnt vmcnt(0) lgkmcnt(0)
	v_cmp_eq_u32_e32 vcc, v2, v0
	s_and_saveexec_b64 s[16:17], vcc
	s_cbranch_execz .LBB0_83
	s_add_u32 s10, s15, 0x19700200
	s_addc_u32 s11, s14, 0
	s_mov_b32 s28, 1
	s_mov_b64 s[18:19], 0
	s_branch .LBB0_76

; __device__ __forceinline__ unsigned xb_ld(unsigned* p)              { return __hip_atomic_load(p, __ATOMIC_RELAXED, __HIP_MEMORY_SCOPE_AGENT); }
; __device__ __forceinline__ unsigned xb_add(unsigned* p, unsigned v) { return __hip_atomic_fetch_add(p, v, __ATOMIC_RELAXED, __HIP_MEMORY_SCOPE_AGENT); }
; #define XB_SPIN(cond, bar) do { unsigned _sp = 0; while (cond) { __builtin_amdgcn_s_sleep(1); \
;     if ((++_sp & 255u) == 0u) { if (xb_ld(&(bar)[XB_TMO])) break; if (_sp > XB_SPIN_CAP) { atomicAdd(&(bar)[XB_TMO], 1u); break; } } } } while (0)
; __device__ __forceinline__ void xcc_barrier(unsigned* bar, unsigned x, unsigned nloc) {
;     ...
;         if (old + 1u == (gen + 1u) * nloc) xb_add(&bar[XL_GEN(x)], 1u); else XB_SPIN(xb_ld(&bar[XL_GEN(x)]) == gen, bar);
;         __builtin_amdgcn_fence(__ATOMIC_ACQUIRE, "agent");
;         asm volatile("s_waitcnt vmcnt(0)" ::: "memory");
;     }
.LBB0_86:
	s_or_b64 exec, exec, s[4:5]
	s_waitcnt vmcnt(0) lgkmcnt(0)
	s_waitcnt vmcnt(0)
